# v23 + P6 first-branch GEMM epilogue: all 16 gate loads issued up front into the dead operand registers (was one load in flight)
# baseline (speedup 1.0000x reference)
; __device__ __forceinline__ unsigned cvt_pk_bf16(float lo, float hi) { unsigned r; asm volatile("v_cvt_pk_bf16_f32 %0, %1, %2" : "=v"(r) : "v"(lo), "v"(hi)); return r; }
;     __device__ __forceinline__ void operator()(const f32x4 (&acc)[2][2][4][2], const Unit& u, int wr, int wc, int fr, int fq) const {
;     ...
;         for (int ai = 0; ai < 2; ++ai)
; #pragma unroll
;             for (int m = 0; m < 4; ++m) {
;                 const size_t row = (size_t)(row0 + ai * HALF + m * 16);
; #pragma unroll
;                 for (int bj = 0; bj < 2; ++bj) {
;                     const int col = col0 + bj * HALF;
;                     f32x4 g0, g1; bf8(*(const u32x4*)(Q + row * QW + (MODE == 0 ? QC_GA : QC_GB) + col), g0, g1);
;                     f32x4 v0 = acc[ai][bj][m][0] * g0, v1 = acc[ai][bj][m][1] * g1;
;                     if (MODE == 1) { f32x4 t0, t1; bf8(*(const u32x4*)(merged + row * D + col), t0, t1); v0 += t0; v1 += t1; }
;                     u32x4 w; w.x = cvt_pk_bf16(v0[0], v0[1]); w.y = cvt_pk_bf16(v0[2], v0[3]); w.z = cvt_pk_bf16(v1[0], v1[1]); w.w = cvt_pk_bf16(v1[2], v1[3]);
;                     *(u32x4*)(merged + row * D + col) = w;
.LBB0_646:
	v_lshl_add_u32 v144, s45, 8, v152
	v_lshl_add_u32 v146, s18, 8, v150
	v_mov_b64_e32 v[148:149], s[60:61]
	v_ashrrev_i32_e32 v145, 31, v144
	v_mad_i64_i32 v[156:157], s[20:21], v146, s44, v[148:149]
	v_lshlrev_b64 v[144:145], 1, v[144:145]
	v_lshl_add_u64 v[160:161], v[156:157], 0, v[144:145]
	v_mov_b32_e32 v232, v146
	v_mad_i64_i32 v[234:235], s[98:99], v232, s44, v[148:149]
	v_lshl_add_u64 v[234:235], v[234:235], 0, v[144:145]
	global_load_dwordx4 v[168:171], v[234:235], off offset:1536 nt
	global_load_dwordx4 v[172:175], v[234:235], off offset:1792 nt
	v_or_b32_e32 v232, 16, v146
	v_mad_i64_i32 v[234:235], s[98:99], v232, s44, v[148:149]
	v_lshl_add_u64 v[234:235], v[234:235], 0, v[144:145]
	global_load_dwordx4 v[176:179], v[234:235], off offset:1536 nt
	global_load_dwordx4 v[180:183], v[234:235], off offset:1792 nt
	v_or_b32_e32 v232, 32, v146
	v_mad_i64_i32 v[234:235], s[98:99], v232, s44, v[148:149]
	v_lshl_add_u64 v[234:235], v[234:235], 0, v[144:145]
	global_load_dwordx4 v[184:187], v[234:235], off offset:1536 nt
	global_load_dwordx4 v[188:191], v[234:235], off offset:1792 nt
	v_or_b32_e32 v232, 48, v146
	v_mad_i64_i32 v[234:235], s[98:99], v232, s44, v[148:149]
	v_lshl_add_u64 v[234:235], v[234:235], 0, v[144:145]
	global_load_dwordx4 v[192:195], v[234:235], off offset:1536 nt
	global_load_dwordx4 v[196:199], v[234:235], off offset:1792 nt
	v_add_u32_e32 v232, 0x80, v146
	v_mad_i64_i32 v[234:235], s[98:99], v232, s44, v[148:149]
	v_lshl_add_u64 v[234:235], v[234:235], 0, v[144:145]
	global_load_dwordx4 v[200:203], v[234:235], off offset:1536 nt
	global_load_dwordx4 v[204:207], v[234:235], off offset:1792 nt
	v_add_u32_e32 v232, 0x90, v146
	v_mad_i64_i32 v[234:235], s[98:99], v232, s44, v[148:149]
	v_lshl_add_u64 v[234:235], v[234:235], 0, v[144:145]
	global_load_dwordx4 v[208:211], v[234:235], off offset:1536 nt
	global_load_dwordx4 v[212:215], v[234:235], off offset:1792 nt
	v_add_u32_e32 v232, 0xa0, v146
	v_mad_i64_i32 v[234:235], s[98:99], v232, s44, v[148:149]
	v_lshl_add_u64 v[234:235], v[234:235], 0, v[144:145]
	global_load_dwordx4 v[216:219], v[234:235], off offset:1536 nt
	global_load_dwordx4 v[220:223], v[234:235], off offset:1792 nt
	v_add_u32_e32 v232, 0xb0, v146
	v_mad_i64_i32 v[234:235], s[98:99], v232, s44, v[148:149]
	v_lshl_add_u64 v[234:235], v[234:235], 0, v[144:145]
	global_load_dwordx4 v[224:227], v[234:235], off offset:1536 nt
	global_load_dwordx4 v[228:231], v[234:235], off offset:1792 nt
	s_nop 0
	v_ashrrev_i32_e32 v147, 31, v146
	v_readlane_b32 s22, v241, 19
	v_readlane_b32 s23, v241, 20
	s_andn2_b64 vcc, exec, s[0:1]
	s_mov_b64 s[0:1], -1
	s_nop 0
	s_waitcnt vmcnt(15)
	v_lshlrev_b32_e32 v162, 16, v168
	v_and_b32_e32 v163, 0xffff0000, v168
	v_lshlrev_b32_e32 v156, 16, v169
	v_and_b32_e32 v157, 0xffff0000, v169
	v_lshlrev_b32_e32 v164, 16, v170
	v_and_b32_e32 v165, 0xffff0000, v170
	v_lshlrev_b32_e32 v158, 16, v171
	v_and_b32_e32 v159, 0xffff0000, v171
	v_pk_mul_f32 v[126:127], v[126:127], v[156:157]
	v_pk_mul_f32 v[124:125], v[124:125], v[162:163]
	v_pk_mul_f32 v[156:157], v[122:123], v[158:159]
	v_pk_mul_f32 v[122:123], v[120:121], v[164:165]
	v_cvt_pk_bf16_f32 v120, v124, v125
	v_cvt_pk_bf16_f32 v121, v126, v127
	v_lshlrev_b64 v[158:159], 11, v[146:147]
	v_cvt_pk_bf16_f32 v122, v122, v123
	v_cvt_pk_bf16_f32 v123, v156, v157
	s_nop 0
	v_lshl_add_u64 v[158:159], s[22:23], 0, v[158:159]
	v_or_b32_e32 v156, 16, v146
	v_lshl_add_u64 v[158:159], v[158:159], 0, v[144:145]
	v_mad_i64_i32 v[160:161], s[20:21], v156, s44, v[148:149]
	global_store_dwordx4 v[158:159], v[120:123], off
	v_lshl_add_u64 v[160:161], v[160:161], 0, v[144:145]
	v_ashrrev_i32_e32 v157, 31, v156
	s_nop 0
	s_waitcnt vmcnt(15)
	v_lshlrev_b32_e32 v120, 16, v172
	v_and_b32_e32 v121, 0xffff0000, v172
	v_lshlrev_b32_e32 v122, 16, v173
	v_and_b32_e32 v123, 0xffff0000, v173
	v_lshlrev_b32_e32 v124, 16, v174
	v_and_b32_e32 v125, 0xffff0000, v174
	v_lshlrev_b32_e32 v126, 16, v175
	v_and_b32_e32 v127, 0xffff0000, v175
	v_pk_mul_f32 v[114:115], v[114:115], v[122:123]
	v_pk_mul_f32 v[112:113], v[112:113], v[120:121]
	v_pk_mul_f32 v[120:121], v[110:111], v[126:127]
	v_pk_mul_f32 v[110:111], v[108:109], v[124:125]
	v_cvt_pk_bf16_f32 v108, v112, v113
	v_cvt_pk_bf16_f32 v109, v114, v115
	s_nop 0
	v_cvt_pk_bf16_f32 v110, v110, v111
	v_cvt_pk_bf16_f32 v111, v120, v121
	s_nop 0
	s_nop 0
	global_store_dwordx4 v[158:159], v[108:111], off offset:256
	s_nop 0
	s_nop 0
	s_waitcnt vmcnt(15)
	v_lshlrev_b32_e32 v108, 16, v176
	v_and_b32_e32 v109, 0xffff0000, v176
	v_lshlrev_b32_e32 v110, 16, v177
	v_and_b32_e32 v111, 0xffff0000, v177
	v_lshlrev_b32_e32 v112, 16, v178
	v_and_b32_e32 v113, 0xffff0000, v178
	v_lshlrev_b32_e32 v114, 16, v179
	v_and_b32_e32 v115, 0xffff0000, v179
	v_pk_mul_f32 v[110:111], v[118:119], v[110:111]
	v_pk_mul_f32 v[108:109], v[116:117], v[108:109]
	v_pk_mul_f32 v[114:115], v[106:107], v[114:115]
	v_pk_mul_f32 v[106:107], v[104:105], v[112:113]
	v_cvt_pk_bf16_f32 v104, v108, v109
	v_cvt_pk_bf16_f32 v105, v110, v111
	v_lshlrev_b64 v[116:117], 11, v[156:157]
	v_cvt_pk_bf16_f32 v106, v106, v107
	v_cvt_pk_bf16_f32 v107, v114, v115
	s_nop 0
	v_lshl_add_u64 v[116:117], s[22:23], 0, v[116:117]
	v_or_b32_e32 v112, 32, v146
	v_lshl_add_u64 v[116:117], v[116:117], 0, v[144:145]
	v_mad_i64_i32 v[114:115], s[20:21], v112, s44, v[148:149]
	global_store_dwordx4 v[116:117], v[104:107], off
	v_lshl_add_u64 v[114:115], v[114:115], 0, v[144:145]
	v_ashrrev_i32_e32 v113, 31, v112
	s_nop 0
	s_waitcnt vmcnt(15)
; __device__ __forceinline__ unsigned cvt_pk_bf16(float lo, float hi) { unsigned r; asm volatile("v_cvt_pk_bf16_f32 %0, %1, %2" : "=v"(r) : "v"(lo), "v"(hi)); return r; }
;     __device__ __forceinline__ void operator()(const f32x4 (&acc)[2][2][4][2], const Unit& u, int wr, int wc, int fr, int fq) const {
;     ...
;         for (int ai = 0; ai < 2; ++ai)
; #pragma unroll
;             for (int m = 0; m < 4; ++m) {
;                 const size_t row = (size_t)(row0 + ai * HALF + m * 16);
; #pragma unroll
;                 for (int bj = 0; bj < 2; ++bj) {
;                     const int col = col0 + bj * HALF;
;                     f32x4 g0, g1; bf8(*(const u32x4*)(Q + row * QW + (MODE == 0 ? QC_GA : QC_GB) + col), g0, g1);
;                     f32x4 v0 = acc[ai][bj][m][0] * g0, v1 = acc[ai][bj][m][1] * g1;
;                     if (MODE == 1) { f32x4 t0, t1; bf8(*(const u32x4*)(merged + row * D + col), t0, t1); v0 += t0; v1 += t1; }
;                     u32x4 w; w.x = cvt_pk_bf16(v0[0], v0[1]); w.y = cvt_pk_bf16(v0[2], v0[3]); w.z = cvt_pk_bf16(v1[0], v1[1]); w.w = cvt_pk_bf16(v1[2], v1[3]);
;                     *(u32x4*)(merged + row * D + col) = w;
	v_lshlrev_b32_e32 v104, 16, v180
	v_and_b32_e32 v105, 0xffff0000, v180
	v_lshlrev_b32_e32 v106, 16, v181
	v_and_b32_e32 v107, 0xffff0000, v181
	v_lshlrev_b32_e32 v108, 16, v182
	v_and_b32_e32 v109, 0xffff0000, v182
	v_lshlrev_b32_e32 v110, 16, v183
	v_and_b32_e32 v111, 0xffff0000, v183
	v_pk_mul_f32 v[98:99], v[98:99], v[106:107]
	v_pk_mul_f32 v[96:97], v[96:97], v[104:105]
	v_pk_mul_f32 v[104:105], v[94:95], v[110:111]
	v_pk_mul_f32 v[94:95], v[92:93], v[108:109]
	v_cvt_pk_bf16_f32 v92, v96, v97
	v_cvt_pk_bf16_f32 v93, v98, v99
	s_nop 0
	v_cvt_pk_bf16_f32 v94, v94, v95
	v_cvt_pk_bf16_f32 v95, v104, v105
	s_nop 0
	s_nop 0
	global_store_dwordx4 v[116:117], v[92:95], off offset:256
	s_nop 0
	s_nop 0
	s_waitcnt vmcnt(15)
	v_lshlrev_b32_e32 v92, 16, v184
	v_and_b32_e32 v93, 0xffff0000, v184
	v_lshlrev_b32_e32 v94, 16, v185
	v_and_b32_e32 v95, 0xffff0000, v185
	v_lshlrev_b32_e32 v96, 16, v186
	v_and_b32_e32 v97, 0xffff0000, v186
	v_lshlrev_b32_e32 v98, 16, v187
	v_and_b32_e32 v99, 0xffff0000, v187
	v_pk_mul_f32 v[94:95], v[102:103], v[94:95]
	v_pk_mul_f32 v[92:93], v[100:101], v[92:93]
	v_pk_mul_f32 v[98:99], v[90:91], v[98:99]
	v_pk_mul_f32 v[90:91], v[88:89], v[96:97]
	v_cvt_pk_bf16_f32 v88, v92, v93
	v_cvt_pk_bf16_f32 v89, v94, v95
	v_lshlrev_b64 v[100:101], 11, v[112:113]
	v_cvt_pk_bf16_f32 v90, v90, v91
	v_cvt_pk_bf16_f32 v91, v98, v99
	s_nop 0
	v_lshl_add_u64 v[100:101], s[22:23], 0, v[100:101]
	v_or_b32_e32 v96, 48, v146
	v_lshl_add_u64 v[100:101], v[100:101], 0, v[144:145]
	v_mad_i64_i32 v[98:99], s[20:21], v96, s44, v[148:149]
	global_store_dwordx4 v[100:101], v[88:91], off
	v_lshl_add_u64 v[98:99], v[98:99], 0, v[144:145]
	v_ashrrev_i32_e32 v97, 31, v96
	s_nop 0
	s_waitcnt vmcnt(15)
	v_lshlrev_b32_e32 v88, 16, v188
	v_and_b32_e32 v89, 0xffff0000, v188
	v_lshlrev_b32_e32 v90, 16, v189
	v_and_b32_e32 v91, 0xffff0000, v189
	v_lshlrev_b32_e32 v92, 16, v190
	v_and_b32_e32 v93, 0xffff0000, v190
	v_lshlrev_b32_e32 v94, 16, v191
	v_and_b32_e32 v95, 0xffff0000, v191
	v_pk_mul_f32 v[82:83], v[82:83], v[90:91]
	v_pk_mul_f32 v[80:81], v[80:81], v[88:89]
	v_pk_mul_f32 v[88:89], v[78:79], v[94:95]
	v_pk_mul_f32 v[78:79], v[76:77], v[92:93]
	v_cvt_pk_bf16_f32 v76, v80, v81
	v_cvt_pk_bf16_f32 v77, v82, v83
	s_nop 0
	v_cvt_pk_bf16_f32 v78, v78, v79
	v_cvt_pk_bf16_f32 v79, v88, v89
	s_nop 0
	s_nop 0
	global_store_dwordx4 v[100:101], v[76:79], off offset:256
	s_nop 0
	s_nop 0
	s_waitcnt vmcnt(15)
	v_lshlrev_b32_e32 v76, 16, v192
	v_and_b32_e32 v77, 0xffff0000, v192
	v_lshlrev_b32_e32 v78, 16, v193
	v_and_b32_e32 v79, 0xffff0000, v193
	v_lshlrev_b32_e32 v80, 16, v194
	v_and_b32_e32 v81, 0xffff0000, v194
	v_lshlrev_b32_e32 v82, 16, v195
	v_and_b32_e32 v83, 0xffff0000, v195
	v_pk_mul_f32 v[78:79], v[86:87], v[78:79]
	v_pk_mul_f32 v[76:77], v[84:85], v[76:77]
	v_pk_mul_f32 v[82:83], v[74:75], v[82:83]
	v_pk_mul_f32 v[74:75], v[72:73], v[80:81]
	v_cvt_pk_bf16_f32 v72, v76, v77
	v_cvt_pk_bf16_f32 v73, v78, v79
	v_lshlrev_b64 v[84:85], 11, v[96:97]
	v_cvt_pk_bf16_f32 v74, v74, v75
	v_cvt_pk_bf16_f32 v75, v82, v83
	s_nop 0
	v_lshl_add_u64 v[84:85], s[22:23], 0, v[84:85]
	v_add_u32_e32 v80, 0x80, v146
	v_lshl_add_u64 v[84:85], v[84:85], 0, v[144:145]
	v_mad_i64_i32 v[82:83], s[20:21], v80, s44, v[148:149]
	global_store_dwordx4 v[84:85], v[72:75], off
	v_lshl_add_u64 v[82:83], v[82:83], 0, v[144:145]
	v_ashrrev_i32_e32 v81, 31, v80
	s_nop 0
	s_waitcnt vmcnt(15)
	v_lshlrev_b32_e32 v72, 16, v196
	v_and_b32_e32 v73, 0xffff0000, v196
	v_lshlrev_b32_e32 v74, 16, v197
	v_and_b32_e32 v75, 0xffff0000, v197
	v_lshlrev_b32_e32 v76, 16, v198
	v_and_b32_e32 v77, 0xffff0000, v198
	v_lshlrev_b32_e32 v78, 16, v199
	v_and_b32_e32 v79, 0xffff0000, v199
	v_pk_mul_f32 v[70:71], v[70:71], v[74:75]
	v_pk_mul_f32 v[68:69], v[68:69], v[72:73]
	v_pk_mul_f32 v[72:73], v[66:67], v[78:79]
	v_pk_mul_f32 v[66:67], v[64:65], v[76:77]
	v_cvt_pk_bf16_f32 v64, v68, v69
	v_cvt_pk_bf16_f32 v65, v70, v71
	s_nop 0
	v_cvt_pk_bf16_f32 v66, v66, v67
	v_cvt_pk_bf16_f32 v67, v72, v73
	s_nop 0
	s_nop 0
	global_store_dwordx4 v[84:85], v[64:67], off offset:256
	s_nop 0
	s_nop 0
	s_waitcnt vmcnt(15)
	v_lshlrev_b32_e32 v64, 16, v200
	v_and_b32_e32 v65, 0xffff0000, v200
	v_lshlrev_b32_e32 v66, 16, v201
	v_and_b32_e32 v67, 0xffff0000, v201
	v_lshlrev_b32_e32 v68, 16, v202
	v_and_b32_e32 v69, 0xffff0000, v202
	v_lshlrev_b32_e32 v70, 16, v203
	v_and_b32_e32 v71, 0xffff0000, v203
	v_pk_mul_f32 v[62:63], v[62:63], v[66:67]
	v_pk_mul_f32 v[60:61], v[60:61], v[64:65]
	v_pk_mul_f32 v[64:65], v[58:59], v[70:71]
	v_pk_mul_f32 v[58:59], v[56:57], v[68:69]
	v_cvt_pk_bf16_f32 v56, v60, v61
	v_cvt_pk_bf16_f32 v57, v62, v63
	v_lshlrev_b64 v[68:69], 11, v[80:81]
	v_cvt_pk_bf16_f32 v58, v58, v59
	v_cvt_pk_bf16_f32 v59, v64, v65
	s_nop 0
	v_lshl_add_u64 v[68:69], s[22:23], 0, v[68:69]
	v_add_u32_e32 v64, 0x90, v146
	v_lshl_add_u64 v[68:69], v[68:69], 0, v[144:145]
	v_mad_i64_i32 v[66:67], s[20:21], v64, s44, v[148:149]
	global_store_dwordx4 v[68:69], v[56:59], off
	v_lshl_add_u64 v[66:67], v[66:67], 0, v[144:145]
	v_ashrrev_i32_e32 v65, 31, v64
	s_nop 0
	s_waitcnt vmcnt(15)
; __device__ __forceinline__ unsigned cvt_pk_bf16(float lo, float hi) { unsigned r; asm volatile("v_cvt_pk_bf16_f32 %0, %1, %2" : "=v"(r) : "v"(lo), "v"(hi)); return r; }
;     __device__ __forceinline__ void operator()(const f32x4 (&acc)[2][2][4][2], const Unit& u, int wr, int wc, int fr, int fq) const {
;     ...
;         for (int ai = 0; ai < 2; ++ai)
; #pragma unroll
;             for (int m = 0; m < 4; ++m) {
;                 const size_t row = (size_t)(row0 + ai * HALF + m * 16);
; #pragma unroll
;                 for (int bj = 0; bj < 2; ++bj) {
;                     const int col = col0 + bj * HALF;
;                     f32x4 g0, g1; bf8(*(const u32x4*)(Q + row * QW + (MODE == 0 ? QC_GA : QC_GB) + col), g0, g1);
;                     f32x4 v0 = acc[ai][bj][m][0] * g0, v1 = acc[ai][bj][m][1] * g1;
;                     if (MODE == 1) { f32x4 t0, t1; bf8(*(const u32x4*)(merged + row * D + col), t0, t1); v0 += t0; v1 += t1; }
;                     u32x4 w; w.x = cvt_pk_bf16(v0[0], v0[1]); w.y = cvt_pk_bf16(v0[2], v0[3]); w.z = cvt_pk_bf16(v1[0], v1[1]); w.w = cvt_pk_bf16(v1[2], v1[3]);
;                     *(u32x4*)(merged + row * D + col) = w;
	v_lshlrev_b32_e32 v56, 16, v204
	v_and_b32_e32 v57, 0xffff0000, v204
	v_lshlrev_b32_e32 v58, 16, v205
	v_and_b32_e32 v59, 0xffff0000, v205
	v_lshlrev_b32_e32 v60, 16, v206
	v_and_b32_e32 v61, 0xffff0000, v206
	v_lshlrev_b32_e32 v62, 16, v207
	v_and_b32_e32 v63, 0xffff0000, v207
	v_pk_mul_f32 v[50:51], v[50:51], v[58:59]
	v_pk_mul_f32 v[48:49], v[48:49], v[56:57]
	v_pk_mul_f32 v[56:57], v[46:47], v[62:63]
	v_pk_mul_f32 v[46:47], v[44:45], v[60:61]
	v_cvt_pk_bf16_f32 v44, v48, v49
	v_cvt_pk_bf16_f32 v45, v50, v51
	s_nop 0
	v_cvt_pk_bf16_f32 v46, v46, v47
	v_cvt_pk_bf16_f32 v47, v56, v57
	s_nop 0
	s_nop 0
	global_store_dwordx4 v[68:69], v[44:47], off offset:256
	s_nop 0
	s_nop 0
	s_waitcnt vmcnt(15)
	v_lshlrev_b32_e32 v44, 16, v208
	v_and_b32_e32 v45, 0xffff0000, v208
	v_lshlrev_b32_e32 v46, 16, v209
	v_and_b32_e32 v47, 0xffff0000, v209
	v_lshlrev_b32_e32 v48, 16, v210
	v_and_b32_e32 v49, 0xffff0000, v210
	v_lshlrev_b32_e32 v50, 16, v211
	v_and_b32_e32 v51, 0xffff0000, v211
	v_pk_mul_f32 v[46:47], v[54:55], v[46:47]
	v_pk_mul_f32 v[44:45], v[52:53], v[44:45]
	v_pk_mul_f32 v[50:51], v[42:43], v[50:51]
	v_pk_mul_f32 v[42:43], v[40:41], v[48:49]
	v_cvt_pk_bf16_f32 v40, v44, v45
	v_cvt_pk_bf16_f32 v41, v46, v47
	v_lshlrev_b64 v[52:53], 11, v[64:65]
	v_cvt_pk_bf16_f32 v42, v42, v43
	v_cvt_pk_bf16_f32 v43, v50, v51
	s_nop 0
	v_lshl_add_u64 v[52:53], s[22:23], 0, v[52:53]
	v_add_u32_e32 v48, 0xa0, v146
	v_lshl_add_u64 v[52:53], v[52:53], 0, v[144:145]
	v_mad_i64_i32 v[50:51], s[20:21], v48, s44, v[148:149]
	global_store_dwordx4 v[52:53], v[40:43], off
	v_lshl_add_u64 v[50:51], v[50:51], 0, v[144:145]
	v_ashrrev_i32_e32 v49, 31, v48
	s_nop 0
	s_waitcnt vmcnt(15)
	v_lshlrev_b32_e32 v40, 16, v212
	v_and_b32_e32 v41, 0xffff0000, v212
	v_lshlrev_b32_e32 v42, 16, v213
	v_and_b32_e32 v43, 0xffff0000, v213
	v_lshlrev_b32_e32 v44, 16, v214
	v_and_b32_e32 v45, 0xffff0000, v214
	v_lshlrev_b32_e32 v46, 16, v215
	v_and_b32_e32 v47, 0xffff0000, v215
	v_pk_mul_f32 v[34:35], v[34:35], v[42:43]
	v_pk_mul_f32 v[32:33], v[32:33], v[40:41]
	v_pk_mul_f32 v[40:41], v[30:31], v[46:47]
	v_pk_mul_f32 v[30:31], v[28:29], v[44:45]
	v_cvt_pk_bf16_f32 v28, v32, v33
	v_cvt_pk_bf16_f32 v29, v34, v35
	s_nop 0
	v_cvt_pk_bf16_f32 v30, v30, v31
	v_cvt_pk_bf16_f32 v31, v40, v41
	s_nop 0
	s_nop 0
	global_store_dwordx4 v[52:53], v[28:31], off offset:256
	s_nop 0
	s_nop 0
	s_waitcnt vmcnt(15)
	v_lshlrev_b32_e32 v28, 16, v216
	v_and_b32_e32 v29, 0xffff0000, v216
	v_lshlrev_b32_e32 v30, 16, v217
	v_and_b32_e32 v31, 0xffff0000, v217
	v_lshlrev_b32_e32 v32, 16, v218
	v_and_b32_e32 v33, 0xffff0000, v218
	v_lshlrev_b32_e32 v34, 16, v219
	v_and_b32_e32 v35, 0xffff0000, v219
	v_pk_mul_f32 v[30:31], v[38:39], v[30:31]
	v_pk_mul_f32 v[28:29], v[36:37], v[28:29]
	v_pk_mul_f32 v[34:35], v[26:27], v[34:35]
	v_pk_mul_f32 v[26:27], v[24:25], v[32:33]
	v_cvt_pk_bf16_f32 v24, v28, v29
	v_cvt_pk_bf16_f32 v25, v30, v31
	v_lshlrev_b64 v[36:37], 11, v[48:49]
	v_cvt_pk_bf16_f32 v26, v26, v27
	v_cvt_pk_bf16_f32 v27, v34, v35
	s_nop 0
	v_lshl_add_u64 v[36:37], s[22:23], 0, v[36:37]
	v_add_u32_e32 v32, 0xb0, v146
	v_lshl_add_u64 v[36:37], v[36:37], 0, v[144:145]
	v_mad_i64_i32 v[34:35], s[20:21], v32, s44, v[148:149]
	global_store_dwordx4 v[36:37], v[24:27], off
	v_lshl_add_u64 v[34:35], v[34:35], 0, v[144:145]
	v_ashrrev_i32_e32 v33, 31, v32
	s_nop 0
	s_waitcnt vmcnt(15)
	v_lshlrev_b32_e32 v24, 16, v220
	v_and_b32_e32 v25, 0xffff0000, v220
	v_lshlrev_b32_e32 v26, 16, v221
	v_and_b32_e32 v27, 0xffff0000, v221
	v_lshlrev_b32_e32 v28, 16, v222
	v_and_b32_e32 v29, 0xffff0000, v222
	v_lshlrev_b32_e32 v30, 16, v223
	v_and_b32_e32 v31, 0xffff0000, v223
	v_pk_mul_f32 v[18:19], v[18:19], v[26:27]
	v_pk_mul_f32 v[16:17], v[16:17], v[24:25]
	v_pk_mul_f32 v[24:25], v[14:15], v[30:31]
	v_pk_mul_f32 v[14:15], v[12:13], v[28:29]
	v_cvt_pk_bf16_f32 v12, v16, v17
	v_cvt_pk_bf16_f32 v13, v18, v19
	s_nop 0
	v_cvt_pk_bf16_f32 v14, v14, v15
	v_cvt_pk_bf16_f32 v15, v24, v25
	s_nop 0
	s_nop 0
	global_store_dwordx4 v[36:37], v[12:15], off offset:256
	s_nop 0
	s_nop 0
	s_waitcnt vmcnt(15)
	v_lshlrev_b32_e32 v12, 16, v224
	v_and_b32_e32 v13, 0xffff0000, v224
	v_lshlrev_b32_e32 v14, 16, v225
	v_and_b32_e32 v15, 0xffff0000, v225
	v_lshlrev_b32_e32 v16, 16, v226
	v_and_b32_e32 v17, 0xffff0000, v226
	v_lshlrev_b32_e32 v18, 16, v227
	v_and_b32_e32 v19, 0xffff0000, v227
	v_pk_mul_f32 v[14:15], v[22:23], v[14:15]
	v_pk_mul_f32 v[12:13], v[20:21], v[12:13]
	v_pk_mul_f32 v[18:19], v[10:11], v[18:19]
	v_pk_mul_f32 v[10:11], v[8:9], v[16:17]
	v_cvt_pk_bf16_f32 v8, v12, v13
	v_cvt_pk_bf16_f32 v9, v14, v15
	v_lshlrev_b64 v[16:17], 11, v[32:33]
	v_cvt_pk_bf16_f32 v10, v10, v11
	v_cvt_pk_bf16_f32 v11, v18, v19
	s_nop 0
	v_lshl_add_u64 v[16:17], s[22:23], 0, v[16:17]
	v_lshl_add_u64 v[16:17], v[16:17], 0, v[144:145]
	global_store_dwordx4 v[16:17], v[8:11], off
	s_nop 0
	s_nop 0
	s_waitcnt vmcnt(15)
	v_lshlrev_b32_e32 v8, 16, v228
	v_and_b32_e32 v9, 0xffff0000, v228
	v_lshlrev_b32_e32 v10, 16, v229
	v_and_b32_e32 v11, 0xffff0000, v229
	v_lshlrev_b32_e32 v12, 16, v230
	v_and_b32_e32 v13, 0xffff0000, v230
	v_lshlrev_b32_e32 v14, 16, v231
	v_and_b32_e32 v15, 0xffff0000, v231
	v_pk_mul_f32 v[4:5], v[4:5], v[8:9]
	v_pk_mul_f32 v[8:9], v[2:3], v[14:15]
	v_pk_mul_f32 v[2:3], v[0:1], v[12:13]
	v_pk_mul_f32 v[6:7], v[6:7], v[10:11]
	v_cvt_pk_bf16_f32 v0, v4, v5
	s_nop 0
	v_cvt_pk_bf16_f32 v1, v6, v7
	v_cvt_pk_bf16_f32 v2, v2, v3
	v_cvt_pk_bf16_f32 v3, v8, v9
	global_store_dwordx4 v[16:17], v[0:3], off offset:256
	s_cbranch_vccnz .LBB0_635
	s_and_b64 vcc, exec, s[62:63]
	s_cbranch_vccnz .LBB0_634
	s_barrier
	s_branch .LBB0_634
